# weight conversion rebalanced: the prep phase converts only layer 0; all four matrices of layer l+1 are converted in the idle tail of layer l's in-projection phase
# speedup vs baseline: 1.0037x; 1.0037x over previous
.LBB0_6:
	s_load_dwordx2 s[18:19], s[0:1], 0xc0
	s_lshl_b32 s2, s93, 3
	v_writelane_b32 v252, s2, 4
	s_load_dwordx16 s[60:75], s[0:1], 0x40
	v_mov_b32_e32 v203, 0x358637bd
	s_waitcnt lgkmcnt(0)
	s_lshl_b32 s33, s18, 3
	s_add_u32 s2, s8, 0x6204000
	s_addc_u32 s3, s9, 0
	v_writelane_b32 v252, s2, 5
	s_lshl_b32 s96, s18, 5
	v_mov_b32_e32 v204, 0x3c0881c4
	v_writelane_b32 v252, s3, 6
	v_writelane_b32 v252, s20, 7
	v_mov_b32_e32 v205, 0xbab64f3b
	v_mov_b32_e32 v206, 1
	v_writelane_b32 v252, s21, 8
	s_lshl_b32 s20, s93, 1
	s_cmpk_lt_i32 s20, 0xda0
	s_cselect_b64 s[2:3], -1, 0
	v_writelane_b32 v252, s2, 9
	v_mov_b32_e32 v215, 0x4000
	v_bfrev_b32_e32 v216, 0.5
	v_writelane_b32 v252, s3, 10
	s_add_u32 s2, s8, 0x16a94000
	s_addc_u32 s3, s9, 0
	s_add_u32 s46, s8, 0x4000
	v_writelane_b32 v252, s2, 11
	s_addc_u32 s47, s9, 0
	v_mov_b32_e32 v217, 0x3e000000
	v_writelane_b32 v252, s3, 12
	s_add_u32 s2, s8, 0x1304000
	s_addc_u32 s3, s9, 0
	v_writelane_b32 v252, s2, 13
	v_mov_b32_e32 v218, 0x4f
	v_mov_b32_e32 v219, 0x5f
	v_writelane_b32 v252, s3, 14
	s_add_u32 s2, s8, 0x804000
	s_addc_u32 s3, s9, 0
	v_writelane_b32 v252, s2, 15
	v_mov_b32_e32 v220, 0x6f
	v_mov_b32_e32 v221, 0xfffff500
	v_writelane_b32 v252, s3, 16
	s_add_u32 s2, s8, 0x604000
	s_addc_u32 s3, s9, 0
	s_lshl_b32 s48, s18, 1
	v_writelane_b32 v252, s2, 17
	s_add_u32 s44, s8, 0x16ac4000
	s_addc_u32 s45, s9, 0
	v_writelane_b32 v252, s3, 18
	s_lshl_b32 s2, s93, 9
	s_lshl_b32 s56, s18, 9
	v_writelane_b32 v252, s2, 19
	s_add_u32 s2, s8, 0xa304000
	s_addc_u32 s3, s9, 0
	v_writelane_b32 v252, s2, 20
	s_cmpk_lt_i32 s93, 0x100
	v_mov_b32_e32 v222, 0x7f800000
	v_writelane_b32 v252, s3, 21
	s_cselect_b64 s[2:3], -1, 0
	v_writelane_b32 v252, s2, 22
	v_not_b32_e32 v223, 63
	v_not_b32_e32 v224, 31
	v_writelane_b32 v252, s3, 23
	s_and_b32 s2, s93, 3
	v_writelane_b32 v252, s2, 24
	s_lshl_b32 s2, s93, 6
	s_and_b32 s2, s2, 0x3f00
	v_writelane_b32 v252, s2, 25
	s_ashr_i32 s2, s93, 31
	v_writelane_b32 v252, s2, 26
	s_lshr_b32 s2, s2, 29
	s_add_i32 s2, s93, s2
	s_ashr_i32 s21, s2, 3
	s_and_b32 s2, s2, -8
	s_sub_i32 s22, s93, s2
	s_lshl_b32 s3, s22, 5
	s_ashr_i32 s2, s18, 31
	s_add_u32 s12, s8, 0xc404000
	v_writelane_b32 v252, s2, 27
	s_addc_u32 s13, s9, 0
	v_writelane_b32 v252, s12, 28
	s_mul_hi_i32 s2, s93, 0x2aaaaaab
	v_mov_b32_e32 v225, 0x7fc00000
	v_writelane_b32 v252, s13, 29
	s_add_u32 s12, s8, 0x16acc000
	s_addc_u32 s13, s9, 0
	v_writelane_b32 v252, s12, 30
	s_movk_i32 s37, 0x4000
	s_mov_b32 s30, 0x18000
	v_writelane_b32 v252, s13, 31
	s_add_u32 s12, s8, 0x12da4000
	s_addc_u32 s13, s9, 0
	s_add_u32 s24, s8, 0x139d4000
	s_addc_u32 s25, s9, 0
	v_writelane_b32 v252, s12, 32
	s_add_u32 s94, s8, 0x15234000
	s_addc_u32 s95, s9, 0
	v_writelane_b32 v252, s13, 33
	s_lshr_b32 s12, s2, 31
	s_add_i32 s15, s2, s12
	s_mul_i32 s2, s15, 6
	s_sub_i32 s23, s93, s2
	s_lshl_b32 s16, s15, 8
	s_lshl_b32 s26, s23, 6
	s_add_i32 s2, s16, 0x100
	s_ashr_i32 s27, s26, 31
	s_cmpk_lt_i32 s93, 0x60
	s_cselect_b64 s[28:29], -1, 0
	v_writelane_b32 v252, s28, 34
	s_lshl_b32 s13, s15, 4
	s_addk_i32 s13, 0x4000
	v_writelane_b32 v252, s29, 35
	v_writelane_b32 v252, s13, 36
	s_sub_i32 s13, s18, s23
	s_add_i32 s13, s13, 5
	s_lshl_b64 s[28:29], s[26:27], 1
	v_writelane_b32 v252, s13, 37
	s_add_u32 s13, s8, s28
	v_writelane_b32 v252, s28, 38
	s_addc_u32 s17, s9, s29
	s_mul_i32 s12, s23, 0x208000
	v_writelane_b32 v252, s29, 39
	s_add_u32 s28, s13, 0xc404500
	s_addc_u32 s29, s17, 0
	v_writelane_b32 v252, s28, 40
	s_add_u32 s12, s8, s12
	s_mov_b32 s31, 0xc000
	v_writelane_b32 v252, s29, 41
	v_writelane_b32 v252, s26, 42
	s_mul_hi_i32 s13, s26, 0x8200
	s_addc_u32 s13, s9, s13
	s_add_u32 s12, s12, 0x12174000
	v_writelane_b32 v252, s27, 43
	s_addc_u32 s13, s13, 0
	v_writelane_b32 v252, s12, 44
	s_mov_b32 s36, 0x30000
	s_movk_i32 s57, 0x1700
	v_writelane_b32 v252, s13, 45
	s_ashr_i32 s12, s23, 31
	v_writelane_b32 v252, s12, 46
	s_cmpk_lt_i32 s93, 0x30c
	s_mul_i32 s12, s22, 0x61
	s_cselect_b64 s[26:27], -1, 0
	s_add_i32 s17, s12, 4
	v_writelane_b32 v252, s26, 47
	s_add_u32 s12, s8, 0x16ac8000
	s_addc_u32 s13, s9, 0
	v_writelane_b32 v252, s27, 48
	v_writelane_b32 v252, s12, 49
	s_movk_i32 s76, 0x104
	s_mov_b32 s77, 0x5c000
	v_writelane_b32 v252, s13, 50
	s_add_u32 s12, s8, 0x14604000
	s_addc_u32 s13, s9, 0
	v_writelane_b32 v252, s12, 51
	s_nop 1
	v_writelane_b32 v252, s13, 52
	s_mul_i32 s12, s18, -3
	s_addk_i32 s12, 0x30c
	s_cmp_gt_i32 s12, 0
	s_cselect_b64 s[26:27], -1, 0
	s_cmp_le_i32 s18, s12
	s_cselect_b64 s[28:29], -1, 0
	v_writelane_b32 v252, s28, 53
	s_cmp_lt_i32 s93, s12
	s_nop 0
	v_writelane_b32 v252, s29, 54
	s_cselect_b64 s[28:29], -1, 0
	s_sub_i32 s13, s93, s12
	v_writelane_b32 v252, s28, 55
	s_cmpk_lt_u32 s13, 0x610
	s_nop 0
	v_writelane_b32 v252, s29, 56
	s_cselect_b64 s[28:29], -1, 0
	v_writelane_b32 v252, s28, 57
	s_sub_i32 s13, s18, s12
	s_lshl_b32 s13, s13, 1
	v_writelane_b32 v252, s29, 58
	v_writelane_b32 v252, s13, 59
	s_cmp_gt_i32 s18, s12
	s_cselect_b64 s[12:13], -1, 0
	v_writelane_b32 v252, s26, 60
	s_and_b64 s[12:13], s[26:27], s[12:13]
	s_cmpk_lt_i32 s93, 0x610
	v_writelane_b32 v252, s27, 61
	v_writelane_b32 v252, s12, 62
	s_mov_b32 s28, 0x800000
	s_movk_i32 s29, 0x6000
	v_writelane_b32 v252, s13, 63
	s_cselect_b64 s[12:13], -1, 0
	v_writelane_b32 v253, s12, 0
	s_cmp_gt_i32 s11, 38
	s_nop 0
	v_writelane_b32 v253, s13, 1
	s_cselect_b64 s[12:13], -1, 0
	v_writelane_b32 v253, s12, 2
	s_nop 1
	v_writelane_b32 v253, s13, 3
	s_add_u32 s12, s8, 0x200
	s_addc_u32 s13, s9, 0
	v_writelane_b32 v253, s12, 4
	s_nop 1
	v_writelane_b32 v253, s13, 5
	s_add_u32 s12, s8, 0x1000
	s_addc_u32 s13, s9, 0
	v_writelane_b32 v253, s12, 6
	s_nop 1
	v_writelane_b32 v253, s13, 7
	s_add_u32 s12, s8, 0x1100
	s_addc_u32 s13, s9, 0
	v_writelane_b32 v253, s12, 8
	s_nop 1
	v_writelane_b32 v253, s13, 9
	s_add_u32 s12, s8, 0x1200
	s_addc_u32 s13, s9, 0
	v_writelane_b32 v253, s12, 10
	s_nop 1
	v_writelane_b32 v253, s13, 11
	s_add_u32 s12, s8, 0x1300
	s_addc_u32 s13, s9, 0
	v_writelane_b32 v253, s12, 12
	s_cmp_eq_u32 s14, 15
	s_nop 0
	v_writelane_b32 v253, s13, 13
	s_cselect_b64 s[12:13], -1, 0
	v_writelane_b32 v253, s12, 14
	s_cmp_eq_u32 s14, 14
	s_nop 0
	v_writelane_b32 v253, s13, 15
	s_cselect_b64 s[12:13], -1, 0
	v_writelane_b32 v253, s12, 16
	s_cmp_eq_u32 s14, 13
	s_nop 0
	v_writelane_b32 v253, s13, 17
	s_cselect_b64 s[12:13], -1, 0
	v_writelane_b32 v253, s12, 18
	s_cmp_eq_u32 s14, 12
	s_nop 0
	v_writelane_b32 v253, s13, 19
	s_cselect_b64 s[12:13], -1, 0
	v_writelane_b32 v253, s12, 20
	s_cmp_eq_u32 s14, 11
	s_nop 0
	v_writelane_b32 v253, s13, 21
	s_cselect_b64 s[12:13], -1, 0
	v_writelane_b32 v253, s12, 22
	s_cmp_eq_u32 s14, 10
	s_nop 0
	v_writelane_b32 v253, s13, 23
	s_cselect_b64 s[12:13], -1, 0
	v_writelane_b32 v253, s12, 24
	s_cmp_eq_u32 s14, 9
	s_nop 0
	v_writelane_b32 v253, s13, 25
	s_cselect_b64 s[12:13], -1, 0
	v_writelane_b32 v253, s12, 26
	s_cmp_eq_u32 s14, 8
	s_nop 0
	v_writelane_b32 v253, s13, 27
	s_cselect_b64 s[12:13], -1, 0
	v_writelane_b32 v253, s12, 28
	s_cmp_eq_u32 s14, 7
	s_nop 0
	v_writelane_b32 v253, s13, 29
	s_cselect_b64 s[12:13], -1, 0
	v_writelane_b32 v253, s12, 30
	s_cmp_eq_u32 s14, 6
	s_nop 0
	v_writelane_b32 v253, s13, 31
	s_cselect_b64 s[12:13], -1, 0
	v_writelane_b32 v253, s12, 32
	s_cmp_eq_u32 s14, 5
	s_nop 0
	v_writelane_b32 v253, s13, 33
	s_cselect_b64 s[12:13], -1, 0
	v_writelane_b32 v253, s12, 34
	s_cmp_eq_u32 s14, 4
	s_nop 0
	v_writelane_b32 v253, s13, 35
	s_cselect_b64 s[12:13], -1, 0
	v_writelane_b32 v253, s12, 36
	s_cmp_eq_u32 s14, 3
	s_nop 0
	v_writelane_b32 v253, s13, 37
	s_cselect_b64 s[12:13], -1, 0
	v_writelane_b32 v253, s12, 38
	s_cmp_eq_u32 s14, 2
	s_nop 0
	v_writelane_b32 v253, s13, 39
	s_cselect_b64 s[12:13], -1, 0
	v_writelane_b32 v253, s12, 40
	s_cmp_eq_u32 s14, 1
	s_nop 0
	v_writelane_b32 v253, s13, 41
	s_cselect_b64 s[12:13], -1, 0
	v_writelane_b32 v253, s12, 42
	s_cmp_eq_u32 s14, 0
	s_nop 0
	v_writelane_b32 v253, s13, 43
	s_cselect_b64 s[12:13], -1, 0
	v_writelane_b32 v253, s12, 44
	s_nop 1
	v_writelane_b32 v253, s13, 45
	s_lshl_b32 s12, s14, 8
	s_add_u32 s12, s8, s12
	s_addc_u32 s13, s9, 0
	s_add_u32 s26, s12, 0x1400
	s_addc_u32 s27, s13, 0
	v_writelane_b32 v253, s26, 46
	s_add_u32 s12, s12, 0x2400
	s_addc_u32 s13, s13, 0
	v_writelane_b32 v253, s27, 47
	v_writelane_b32 v253, s12, 48
	s_mov_b64 s[26:27], 0x400
	s_nop 0
	v_writelane_b32 v253, s13, 49
	s_add_u32 s12, s8, 0x3400
	s_addc_u32 s13, s9, 0
	v_writelane_b32 v253, s12, 50
	s_nop 1
	v_writelane_b32 v253, s13, 51
	s_add_u32 s12, s8, 0x3500
	s_addc_u32 s13, s9, 0
	v_writelane_b32 v253, s12, 52
	s_cmp_lt_i32 s22, 0
	s_nop 0
	v_writelane_b32 v253, s13, 53
	s_mul_i32 s12, s22, 33
	s_cselect_b32 s3, s12, s3
	s_add_i32 s3, s3, s21
	s_ashr_i32 s12, s3, 31
	s_lshr_b32 s12, s12, 27
	s_add_i32 s12, s3, s12
	s_and_b32 s13, s12, 0xffe0
	s_sub_i32 s3, s3, s13
	s_bfe_i32 s13, s3, 0x80000
	s_bfe_u32 s13, s13, 0x3000c
	s_add_i32 s13, s3, s13
	s_and_b32 s14, s13, 0xf8
	s_sub_i32 s3, s3, s14
	s_ashr_i32 s12, s12, 5
	s_lshl_b32 s12, s12, 3
	s_sext_i32_i8 s3, s3
	s_add_i32 s3, s12, s3
	v_writelane_b32 v253, s3, 54
	s_bfe_i32 s3, s13, 0x80000
	s_sext_i32_i16 s3, s3
	s_ashr_i32 s3, s3, 3
	v_writelane_b32 v253, s3, 55
	s_cmp_lt_i32 s22, 4
	s_mul_i32 s3, s22, 0x62
	s_cselect_b32 s3, s3, s17
	s_add_i32 s3, s3, s21
	s_mul_hi_i32 s12, s3, 0x2aaaaaab
	s_lshr_b32 s13, s12, 31
	s_ashr_i32 s12, s12, 4
	s_add_i32 s12, s12, s13
	s_mul_i32 s13, s12, 0x60
	s_lshl_b32 s12, s12, 3
	s_sub_i32 s13, s3, s13
	s_sub_i32 s3, 0x41, s12
	s_min_u32 s14, s3, 8
	v_cvt_f32_ubyte0_e32 v2, s14
	v_writelane_b32 v253, s22, 56
	v_cvt_f32_i32_e32 v1, s13
	v_rcp_iflag_f32_e32 v3, v2
	v_writelane_b32 v253, s21, 57
	s_bfe_i32 s3, s15, 0x10017
	v_writelane_b32 v253, s3, 58
	s_abs_i32 s3, s16
	v_writelane_b32 v253, s3, 59
	s_xor_b32 s3, s16, 0xffffff00
	s_max_i32 s3, s2, s3
	v_mul_f32_e32 v3, v1, v3
	v_writelane_b32 v253, s3, 60
	s_ashr_i32 s2, s2, 31
	v_trunc_f32_e32 v3, v3
	v_writelane_b32 v253, s2, 61
	s_ashr_i32 s2, s13, 30
	v_fma_f32 v1, -v3, v2, v1
	s_or_b32 s15, s2, 1
	v_cmp_ge_f32_e64 s[2:3], |v1|, v2
	s_and_b64 s[2:3], s[2:3], exec
	v_lshrrev_b32_e32 v1, 20, v0
	v_lshrrev_b32_e32 v0, 10, v0
	s_load_dword s3, s[0:1], 0xc8
	v_or_b32_e32 v0, v0, v1
	v_cvt_i32_f32_e32 v1, v3
	s_movk_i32 s2, 0x3ff
	v_and_or_b32 v0, v0, s2, v202
	s_mul_i32 s2, s19, s18
	s_waitcnt lgkmcnt(0)
	s_mul_i32 s49, s2, s3
	s_cselect_b32 s2, s15, 0
	v_readfirstlane_b32 s3, v1
	s_add_i32 s2, s3, s2
	s_mul_i32 s3, s2, s14
	s_sub_i32 s3, s13, s3
	s_sext_i32_i8 s3, s3
	s_add_i32 s3, s12, s3
	v_writelane_b32 v253, s3, 62
	s_sext_i32_i8 s2, s2
	v_writelane_b32 v253, s2, 63
	s_lshl_b32 s2, s18, 4
	v_writelane_b32 v254, s2, 0
	s_lshl_b32 s2, s93, 8
	s_ashr_i32 s97, s96, 31
	v_writelane_b32 v254, s2, 1
	s_lshl_b32 s2, s18, 8
	v_writelane_b32 v254, s2, 2
	s_lshl_b64 s[12:13], s[96:97], 12
	s_mul_i32 s2, s23, 0x744
	v_writelane_b32 v254, s12, 3
	s_add_u32 s2, s64, s2
	v_mov_b32_e32 v1, 0
	v_writelane_b32 v254, s13, 4
	v_writelane_b32 v254, s2, 5
	v_writelane_b32 v254, s23, 6
	v_writelane_b32 v254, s60, 7
	s_mul_hi_i32 s2, s23, 0x744
	s_addc_u32 s2, s65, s2
	v_writelane_b32 v254, s61, 8
	v_writelane_b32 v254, s62, 9
	v_writelane_b32 v254, s63, 10
	v_writelane_b32 v254, s64, 11
	v_writelane_b32 v254, s65, 12
	v_writelane_b32 v254, s66, 13
	v_writelane_b32 v254, s67, 14
	v_writelane_b32 v254, s68, 15
	v_writelane_b32 v254, s69, 16
	v_writelane_b32 v254, s70, 17
	v_writelane_b32 v254, s71, 18
	v_writelane_b32 v254, s72, 19
	v_writelane_b32 v254, s73, 20
	v_writelane_b32 v254, s74, 21
	v_writelane_b32 v254, s75, 22
	v_writelane_b32 v254, s2, 23
	s_mul_i32 s2, s18, 6
	s_add_i32 s2, s2, s20
	s_add_i32 s3, s2, 0xfffff9e8
	v_writelane_b32 v254, s3, 24
	s_addk_i32 s2, 0xf9e8
	v_writelane_b32 v254, s2, 25
	s_mul_i32 s2, s18, 24
	v_writelane_b32 v254, s2, 26
	s_add_i32 s2, s96, 0xffffe7a0
	v_writelane_b32 v254, s2, 27
	s_add_i32 s2, s56, 0xfffe7a00
	v_writelane_b32 v254, s2, 28
	v_writelane_b32 v254, s20, 29
	s_add_i32 s2, s20, 0
	v_writelane_b32 v254, s2, 30
	s_lshl_b32 s2, s18, 7
	v_writelane_b32 v254, s2, 31
	s_add_i32 s2, 0, 0x820
	v_writelane_b32 v254, s2, 32
	s_add_i32 s2, 0, 0x5140
	v_writelane_b32 v254, s2, 33
	s_add_i32 s2, 0, 0x20800
	v_writelane_b32 v254, s2, 34
	s_add_i32 s2, 0, 0x201b0
	v_writelane_b32 v254, s2, 35
	s_add_i32 s2, 0, 0x21000
	v_writelane_b32 v254, s2, 36
	s_add_i32 s2, 0, 0x21004
	v_writelane_b32 v254, s2, 37
	s_mov_b32 s3, 0
	s_load_dwordx16 s[60:75], s[0:1], 0x0
	v_writelane_b32 v254, s2, 38
	s_mov_b32 s0, s96
	v_mbcnt_lo_u32_b32 v2, -1, 0
	v_writelane_b32 v254, s3, 39
	v_cmp_eq_u32_e64 s[2:3], 0, v0
	v_mbcnt_hi_u32_b32 v207, -1, v2
	v_and_b32_e32 v2, 64, v207
	v_writelane_b32 v254, s2, 40
	v_add_u32_e32 v208, 64, v2
	v_xor_b32_e32 v209, 32, v207
	v_writelane_b32 v254, s3, 41
	s_waitcnt lgkmcnt(0)
	v_writelane_b32 v254, s60, 42
	v_xor_b32_e32 v210, 16, v207
	v_xor_b32_e32 v211, 8, v207
	v_writelane_b32 v254, s61, 43
	v_writelane_b32 v254, s62, 44
	v_writelane_b32 v254, s63, 45
	v_writelane_b32 v254, s64, 46
	v_writelane_b32 v254, s65, 47
	v_writelane_b32 v254, s66, 48
	v_writelane_b32 v254, s67, 49
	v_writelane_b32 v254, s68, 50
	v_writelane_b32 v254, s69, 51
	v_writelane_b32 v254, s70, 52
	v_writelane_b32 v254, s71, 53
	v_writelane_b32 v254, s72, 54
	v_writelane_b32 v254, s73, 55
	v_writelane_b32 v254, s74, 56
	v_writelane_b32 v254, s75, 57
	v_writelane_b32 v254, s93, 58
	v_writelane_b32 v254, s84, 59
	v_xor_b32_e32 v212, 4, v207
	v_xor_b32_e32 v213, 2, v207
	v_writelane_b32 v255, s89, 0
	v_writelane_b32 v255, s90, 1
	v_writelane_b32 v255, s91, 2
	v_writelane_b32 v255, s0, 3
	v_writelane_b32 v254, s85, 60
	v_writelane_b32 v254, s86, 61
	v_writelane_b32 v255, s1, 4
	v_writelane_b32 v255, s46, 5
	v_writelane_b32 v254, s87, 62
	v_xor_b32_e32 v214, 1, v207
	v_writelane_b32 v255, s47, 6
	v_writelane_b32 v255, s48, 7
	v_writelane_b32 v255, s44, 8
	v_mov_b32_e32 v238, v1
	v_mov_b32_e32 v239, v1
	v_writelane_b32 v255, s45, 9
	v_writelane_b32 v255, s49, 10
	v_mov_b32_e32 v240, v1
	v_mov_b32_e32 v241, v1
	s_mov_b64 s[20:21], 0x80
	v_writelane_b32 v254, s88, 63
	v_writelane_b32 v255, s56, 11
	s_branch .LBB0_10

.LBB0_28:
	s_or_b64 exec, exec, s[12:13]
	s_add_i32 s18, s18, s48
	s_cmpk_gt_i32 s18, 0xd9f
	s_waitcnt lgkmcnt(0)
	s_cbranch_scc1 .LBB0_61
.LBB0_29:
	v_add_u32_e32 v0, s18, v49
	s_movk_i32 s0, 0xc1f
	v_cmp_lt_i32_e32 vcc, s0, v0
	s_and_saveexec_b64 s[0:1], vcc
	s_xor_b64 s[0:1], exec, s[0:1]
	s_cbranch_execz .LBB0_37
	s_mov_b64 s[2:3], 0
	v_mov_b64_e32 v[2:3], v[64:65]
	v_mov_b64_e32 v[4:5], v[62:63]
	v_mov_b32_e32 v6, v88
	v_mov_b32_e32 v7, v87
.LBB0_31:
	global_load_dword v8, v[4:5], off
	global_load_dword v9, v[2:3], off
	v_add_u32_e32 v7, 0x100, v7
	s_movk_i32 s12, 0x2ff
	v_cmp_lt_u32_e32 vcc, s12, v7
	v_lshl_add_u64 v[4:5], v[4:5], 0, s[26:27]
	v_lshl_add_u64 v[2:3], v[2:3], 0, s[26:27]
	s_or_b64 s[2:3], vcc, s[2:3]
	s_waitcnt vmcnt(0)
	v_mul_f32_e32 v10, 0xbfb8aa3b, v8
	v_mul_f32_e32 v11, 0xbfb8aa3b, v9
	v_exp_f32_e32 v10, v10
	v_exp_f32_e32 v11, v11
	v_add_f32_e32 v10, 1.0, v10
	v_add_f32_e32 v11, 1.0, v11
	v_rcp_f32_e32 v10, v10
	v_rcp_f32_e32 v11, v11
	v_mul_f32_e32 v8, v8, v10
	v_mul_f32_e32 v9, v9, v11
	ds_write2st64_b32 v6, v8, v9 offset1:16
	v_add_u32_e32 v6, 0x400, v6
	s_andn2_b64 exec, exec, s[2:3]
	s_cbranch_execnz .LBB0_31
	s_or_b64 exec, exec, s[2:3]
	v_add_u32_e32 v2, 0xfffff3e0, v0
	s_mov_b32 s2, 0xaaaaaaab
	v_mul_hi_u32 v0, v2, s2
	v_lshrrev_b32_e32 v0, 6, v0
	s_movk_i32 s2, 0x60
	v_mul_lo_u32 v3, v0, s2
	v_sub_u32_e32 v2, v2, v3
	v_readlane_b32 s60, v254, 42
	v_lshlrev_b32_e32 v70, 6, v2
	v_lshlrev_b64 v[2:3], 10, v[0:1]
	v_readlane_b32 s68, v254, 50
	v_readlane_b32 s69, v254, 51
	v_or_b32_e32 v2, v2, v46
	v_mov_b32_e32 v71, v1
	v_mov_b64_e32 v[4:5], s[68:69]
	v_mad_u64_u32 v[4:5], s[2:3], v2, s29, v[4:5]
	v_mad_u32_u24 v5, v3, s29, v5
	v_lshl_add_u64 v[2:3], v[70:71], 2, v[4:5]
	v_mov_b32_e32 v67, v1
	v_mov_b32_e32 v8, 0
	v_lshl_add_u64 v[72:73], v[2:3], 0, v[66:67]
	s_mov_b32 s2, -16
	v_mov_b32_e32 v67, v89
	v_mov_b32_e32 v9, v8
	v_mov_b32_e32 v6, v8
	v_mov_b32_e32 v7, v8
	v_mov_b32_e32 v4, v8
	v_mov_b32_e32 v5, v8
	v_mov_b32_e32 v2, v8
	v_mov_b32_e32 v3, v8
	s_waitcnt lgkmcnt(0)
	s_barrier
	v_readlane_b32 s61, v254, 43
	v_readlane_b32 s62, v254, 44
	v_readlane_b32 s63, v254, 45
	v_readlane_b32 s64, v254, 46
	v_readlane_b32 s65, v254, 47
	v_readlane_b32 s66, v254, 48
	v_readlane_b32 s67, v254, 49
	v_readlane_b32 s70, v254, 52
	v_readlane_b32 s71, v254, 53
	v_readlane_b32 s72, v254, 54
	v_readlane_b32 s73, v254, 55
	v_readlane_b32 s74, v254, 56
	v_readlane_b32 s75, v254, 57

.LBB0_485:
	s_or_b64 exec, exec, s[34:35]
	v_readlane_b32 s2, v252, 59
	s_add_i32 s1, s1, s2
	v_readlane_b32 s2, v254, 27
	s_cmpk_gt_i32 s1, 0xc1f
	s_nop 0
	v_add_u32_e32 v26, s2, v26
	v_readlane_b32 s2, v254, 28
	s_nop 1
	v_add_u32_e32 v27, s2, v27
	s_cbranch_scc1 .LBB0_498
.LBB0_486:
	v_add_u32_e32 v0, s1, v11
	s_nop 0
	s_movk_i32 s2, 0x2df
	v_cmp_lt_i32_e32 vcc, s2, v0
	s_and_saveexec_b64 s[2:3], vcc
	s_xor_b64 s[34:35], exec, s[2:3]
	s_cbranch_execz .LBB0_496
	s_movk_i32 s2, 0x3df
	v_cmp_lt_u32_e32 vcc, s2, v0
	s_and_saveexec_b64 s[2:3], vcc
	s_xor_b64 s[38:39], exec, s[2:3]
	s_cbranch_execz .LBB0_493
	s_movk_i32 s2, 0x95f
	v_cmp_lt_u32_e32 vcc, s2, v0
	s_and_saveexec_b64 s[2:3], vcc
	s_xor_b64 s[40:41], exec, s[2:3]
	s_cbranch_execz .LBB0_490
	v_and_b32_e32 v0, 0x7fffffc0, v26
	v_add_u32_e32 v6, 0xffffda80, v0
	v_and_b32_e32 v7, 0x3c0, v27
	v_or_b32_e32 v2, v6, v20
	v_lshlrev_b32_e32 v0, 2, v7
	v_lshl_add_u64 v[4:5], v[12:13], 0, v[0:1]
	v_or_b32_e32 v0, 16, v2
	v_lshlrev_b64 v[28:29], 12, v[0:1]
	v_or_b32_e32 v0, 32, v2
	v_mov_b32_e32 v3, v1
	v_lshl_add_u64 v[36:37], v[4:5], 0, v[28:29]
	v_lshlrev_b64 v[28:29], 12, v[0:1]
	v_or_b32_e32 v0, 48, v2
	v_lshlrev_b64 v[8:9], 12, v[2:3]
	v_lshlrev_b64 v[2:3], 12, v[0:1]
	v_lshl_add_u64 v[8:9], v[4:5], 0, v[8:9]
	v_lshl_add_u64 v[32:33], v[4:5], 0, v[28:29]
	v_lshl_add_u64 v[28:29], v[4:5], 0, v[2:3]
	global_load_dwordx4 v[2:5], v[8:9], off
	s_nop 0
	global_load_dwordx4 v[28:31], v[28:29], off
	s_nop 0
	global_load_dwordx4 v[32:35], v[32:33], off
	s_nop 0
	global_load_dwordx4 v[36:39], v[36:37], off
	v_add_u32_e32 v0, v21, v22
	s_waitcnt vmcnt(0)
	ds_write2_b32 v0, v2, v3 offset1:1
	ds_write2_b32 v0, v4, v5 offset0:2 offset1:3
	v_add_u32_e32 v2, 0x1040, v0
	ds_write2_b32 v2, v36, v37 offset1:1
	v_add_u32_e32 v2, 0x1048, v0
	ds_write2_b32 v2, v38, v39 offset1:1
	v_add_u32_e32 v2, 0x2080, v0
	ds_write2_b32 v2, v32, v33 offset1:1
	v_add_u32_e32 v2, 0x2088, v0
	ds_write2_b32 v2, v34, v35 offset1:1
	v_add_u32_e32 v2, 0x30c0, v0
	v_add_u32_e32 v0, 0x30c8, v0
	ds_write2_b32 v2, v28, v29 offset1:1
	ds_write2_b32 v0, v30, v31 offset1:1
	s_waitcnt lgkmcnt(0)
	s_barrier
	ds_read2_b32 v[2:3], v24 offset1:65
	ds_read2_b32 v[4:5], v24 offset0:130 offset1:195
	v_add_u32_e32 v0, 0x400, v24
	s_waitcnt lgkmcnt(1)
	v_cvt_pk_bf16_f32 v2, v2, v3
	s_waitcnt lgkmcnt(0)
	v_cvt_pk_bf16_f32 v3, v4, v5
	ds_read2_b32 v[4:5], v0 offset0:4 offset1:69
	ds_read2_b32 v[8:9], v0 offset0:134 offset1:199
	v_add_u32_e32 v0, 0x800, v24
	s_waitcnt lgkmcnt(1)
	v_cvt_pk_bf16_f32 v4, v4, v5
	s_waitcnt lgkmcnt(0)
	v_cvt_pk_bf16_f32 v5, v8, v9
	ds_read2_b32 v[8:9], v0 offset0:8 offset1:73
	s_waitcnt lgkmcnt(0)
	v_cvt_pk_bf16_f32 v28, v8, v9
	ds_read2_b32 v[8:9], v0 offset0:138 offset1:203
	v_add_u32_e32 v0, 0xc00, v24
	s_waitcnt lgkmcnt(0)
	v_cvt_pk_bf16_f32 v29, v8, v9
	ds_read2_b32 v[8:9], v0 offset0:12 offset1:77
	s_waitcnt lgkmcnt(0)
	v_cvt_pk_bf16_f32 v30, v8, v9
	ds_read2_b32 v[8:9], v0 offset0:142 offset1:207
	v_or_b32_e32 v0, v7, v23
	v_mul_u32_u24_e32 v0, 0xb00, v0
	v_lshlrev_b32_e32 v0, 1, v0
	s_waitcnt lgkmcnt(0)
	v_cvt_pk_bf16_f32 v31, v8, v9
	v_lshl_add_u64 v[8:9], s[16:17], 0, v[0:1]
	v_mov_b32_e32 v7, v1
	v_lshl_add_u64 v[6:7], v[6:7], 1, v[8:9]
	v_lshlrev_b32_e32 v0, 1, v10
	v_lshl_add_u64 v[6:7], v[6:7], 0, v[0:1]
	global_store_dwordx4 v[6:7], v[2:5], off
	global_store_dwordx4 v[6:7], v[28:31], off offset:16
	s_barrier

.LBB0_499:
	s_andn2_b64 vcc, exec, s[2:3]
	s_cbranch_vccnz .LBB0_522
	v_readlane_b32 s12, v252, 62
	s_xor_b64 s[2:3], s[50:51], -1
	v_readlane_b32 s13, v252, 63
	s_or_b64 s[2:3], s[2:3], s[12:13]
	s_and_b64 vcc, exec, s[2:3]
	s_cbranch_vccnz .LBB0_522
	v_readlane_b32 s2, v253, 0
	v_readlane_b32 s3, v253, 1
	v_mov_b32_e32 v2, v202
	s_andn2_b64 vcc, exec, s[2:3]
	s_waitcnt vmcnt(0) lgkmcnt(0)
	s_barrier
	s_cbranch_vccnz .LBB0_522
	s_ashr_i32 s1, s0, 31
	s_mul_i32 s13, s0, 0x1880000
	s_lshl_b64 s[2:3], s[0:1], 22
	s_mul_hi_i32 s12, s0, 0x1880000
	s_mul_hi_i32 s14, s0, 0xb00000
	s_mul_i32 s15, s0, 0xb00000
	s_mul_hi_i32 s19, s0, 0x1600000
	s_mul_i32 s18, s0, 0x1600000
	s_mul_hi_i32 s22, s0, 0xb80000
	s_mul_i32 s23, s0, 0xb80000
	s_add_u32 s0, s46, s13
	s_addc_u32 s1, s47, s12
	s_add_u32 s16, s90, s15
	s_addc_u32 s17, s91, s14
	s_add_u32 s14, s0, 0x1300000
	s_addc_u32 s15, s1, 0
	v_lshlrev_b32_e32 v6, 4, v2
	s_add_u32 s18, s84, s18
	v_and_b32_e32 v0, 0xf0, v6
	s_addc_u32 s19, s85, s19
	v_lshl_add_u64 v[12:13], s[16:17], 0, v[0:1]
	s_add_u32 s16, s0, 0x800000
	v_readlane_b32 s60, v254, 7
	s_addc_u32 s17, s1, 0
	v_readlane_b32 s72, v254, 19
	v_readlane_b32 s73, v254, 20
	s_add_u32 s2, s72, s2
	v_readlane_b32 s61, v254, 8
	v_readlane_b32 s62, v254, 9
	v_readlane_b32 s63, v254, 10
	v_readlane_b32 s64, v254, 11
	v_readlane_b32 s65, v254, 12
	v_readlane_b32 s66, v254, 13
	v_readlane_b32 s67, v254, 14
	v_readlane_b32 s68, v254, 15
	v_readlane_b32 s69, v254, 16
	v_readlane_b32 s70, v254, 17
	v_readlane_b32 s71, v254, 18
	v_readlane_b32 s74, v254, 21
	v_readlane_b32 s75, v254, 22
	s_addc_u32 s3, s73, s3
	v_lshl_add_u64 v[14:15], s[18:19], 0, v[0:1]
	s_add_u32 s18, s0, 0x600000
	v_readlane_b32 s60, v254, 42
	s_addc_u32 s19, s1, 0
	v_readlane_b32 s74, v254, 56
	v_lshl_add_u64 v[16:17], s[2:3], 0, v[0:1]
	v_readlane_b32 s75, v254, 57
	s_add_u32 s2, s74, s23
	v_ashrrev_i32_e32 v3, 8, v2
	s_addc_u32 s3, s75, s22
	v_lshl_add_u32 v4, v3, 15, 0
	v_and_b32_e32 v10, 48, v6
	v_lshl_add_u64 v[18:19], s[2:3], 0, v[0:1]
	v_readlane_b32 s2, v254, 30
	v_and_b32_e32 v5, 0xff, v2
	v_bfe_u32 v11, v2, 4, 4
	v_add_u32_e32 v20, v4, v0
	v_bfe_u32 v22, v2, 2, 6
	v_mul_u32_u24_e32 v6, 0x104, v10
	v_and_b32_e32 v2, 0xfc, v2
	v_add_u32_e32 v0, s2, v3
	v_mul_u32_u24_e32 v21, 0x104, v11
	v_add3_u32 v23, v4, v6, v2
	v_bfe_u32 v24, v5, 2, 4
	v_mov_b32_e32 v25, v3
	v_lshlrev_b32_e32 v26, 2, v0
	v_lshlrev_b32_e32 v27, 6, v0
	v_readlane_b32 s2, v254, 29
	v_readlane_b32 s61, v254, 43
	v_readlane_b32 s62, v254, 44
	v_readlane_b32 s63, v254, 45
	v_readlane_b32 s64, v254, 46
	v_readlane_b32 s65, v254, 47
	v_readlane_b32 s66, v254, 48
	v_readlane_b32 s67, v254, 49
	v_readlane_b32 s68, v254, 50
	v_readlane_b32 s69, v254, 51
	v_readlane_b32 s70, v254, 52
	v_readlane_b32 s71, v254, 53
	v_readlane_b32 s72, v254, 54
	v_readlane_b32 s73, v254, 55
	s_branch .LBB0_504
.LBB0_503:
	s_or_b64 exec, exec, s[22:23]
	s_add_i32 s2, s2, s48
	v_readlane_b32 s3, v254, 31
	v_add_u32_e32 v26, s33, v26
	s_cmpk_gt_i32 s2, 0xc1f
	v_add_u32_e32 v27, s3, v27
	s_cbranch_scc1 .LBB0_521
